# seam leaders: drop dead XGEN add + its drain, start acquire invalidate without waiting on TOPGEN add
# baseline (speedup 1.0000x reference)
.LBB0_146:
	s_or_b64 exec, exec, s[8:9]
	v_mov_b32_e32 v0, 0x2000
	v_mov_b32_e32 v1, 1
	buffer_inv sc1
	s_waitcnt vmcnt(0)

.LBB0_398:
	s_or_b64 exec, exec, s[4:5]
	v_readlane_b32 s4, v253, 13
	v_readlane_b32 s5, v253, 14
	v_mov_b32_e32 v0, 1
	buffer_inv sc1
	s_waitcnt vmcnt(0)

.LBB0_1273:
	s_or_b64 exec, exec, s[6:7]
	v_readlane_b32 s6, v253, 13
	v_mov_b32_e32 v0, 0
	v_mov_b32_e32 v1, 1
	v_readlane_b32 s7, v253, 14
	buffer_inv sc1
	s_waitcnt vmcnt(0)

.LBB0_1339:
	s_or_b64 exec, exec, s[4:5]
	v_readlane_b32 s4, v253, 13
	v_mov_b32_e32 v0, 0
	v_mov_b32_e32 v1, 1
	v_readlane_b32 s5, v253, 14
	buffer_inv sc1
	s_waitcnt vmcnt(0)

.LBB0_1342:
	s_or_b64 exec, exec, s[4:5]
	v_readlane_b32 s4, v253, 13
	v_readlane_b32 s5, v253, 14
	buffer_inv sc1
	s_waitcnt vmcnt(0)
